# prepB transposes: touch-prefetch of tile t+2G after issuing tile t+G loads (2 tiles in flight per WG)
# baseline (speedup 1.0000x reference)
.LBB0_97:
	s_cmpk_lt_i32 s85, 0x400
	v_mov_b32_e32 v10, v170
	s_cselect_b64 s[0:1], -1, 0
	s_cmpk_gt_i32 s85, 0x3ff
	s_cbranch_scc1 .LBB0_102
	s_add_u32 s3, s42, 0x8400000
	s_addc_u32 s6, s43, 0
	s_ashr_i32 s4, s85, 31
	s_lshr_b32 s4, s4, 23
	s_add_i32 s5, s85, s4
	s_ashr_i32 s4, s5, 9
	s_and_b32 s5, s5, 0xfe00
	s_sub_i32 s5, s85, s5
	s_sext_i32_i16 s7, s5
	s_bfe_u32 s7, s7, 0x5001a
	s_add_i32 s7, s5, s7
	s_sext_i32_i16 s8, s7
	s_and_b32 s7, s7, 0xffe0
	s_sub_i32 s5, s5, s7
	s_sext_i32_i16 s7, s5
	s_ashr_i32 s5, s4, 31
	v_readlane_b32 s12, v252, 4
	s_lshl_b64 s[4:5], s[4:5], 24
	v_readlane_b32 s14, v252, 6
	v_readlane_b32 s15, v252, 7
	s_add_u32 s9, s14, s4
	s_addc_u32 s12, s15, s5
	s_lshl_b32 s4, s8, 1
	s_and_b32 s8, s4, 0xffffffc0
	s_lshl_b32 s4, s7, 6
	s_ashr_i32 s5, s4, 31
	s_lshl_b64 s[4:5], s[4:5], 2
	v_lshlrev_b32_e32 v0, 2, v10
	s_add_u32 s4, s9, s4
	v_and_b32_e32 v18, 60, v0
	v_ashrrev_i32_e32 v12, 4, v10
	s_addc_u32 s5, s12, s5
	v_mov_b32_e32 v9, 0
	v_lshlrev_b32_e32 v8, 2, v18
	v_add_u32_e32 v2, s8, v12
	v_lshl_add_u64 v[0:1], s[4:5], 0, v[8:9]
	s_mov_b64 s[4:5], 0x2000
	v_ashrrev_i32_e32 v3, 31, v2
	v_lshl_add_u64 v[0:1], v[0:1], 0, s[4:5]
	v_lshlrev_b64 v[2:3], 14, v[2:3]
	v_lshl_add_u64 v[14:15], v[0:1], 0, v[2:3]
	v_add_u32_e32 v2, 0x200, v10
	v_ashrrev_i32_e32 v13, 4, v2
	v_add_u32_e32 v2, s8, v13
	v_ashrrev_i32_e32 v3, 31, v2
	v_lshlrev_b64 v[2:3], 14, v[2:3]
	v_lshl_add_u64 v[16:17], v[0:1], 0, v[2:3]
	global_load_dwordx4 v[0:3], v[14:15], off nt
	global_load_dwordx4 v[4:7], v[16:17], off nt
	global_load_dword v48, v[16:17], off
	global_load_dword v48, v[16:17], off
	global_load_dword v48, v[16:17], off
	v_add_u32_e32 v11, 0, v8
	v_lshlrev_b32_e32 v8, 3, v10
	v_ashrrev_i32_e32 v14, 3, v10
	v_and_b32_e32 v8, 56, v8
	s_movk_i32 s4, 0x104
	v_mul_u32_u24_e32 v10, 0x104, v8
	v_lshlrev_b32_e32 v15, 2, v14
	s_add_u32 s7, s14, 0x2000
	v_add3_u32 v15, 0, v10, v15
	v_mul_lo_u32 v10, v12, s4
	v_mul_lo_u32 v17, v13, s4
	s_addc_u32 s8, s15, 0
	v_add_u32_e32 v16, v11, v10
	v_add_u32_e32 v17, v11, v17
	v_lshlrev_b32_e32 v10, 2, v18
	v_lshlrev_b32_e32 v8, 1, v8
	s_mov_b32 s12, s85
	v_readlane_b32 s13, v252, 5
	v_readlane_b32 s16, v252, 8
	v_readlane_b32 s17, v252, 9
	v_readlane_b32 s18, v252, 10
	v_readlane_b32 s19, v252, 11
	v_readlane_b32 s20, v252, 12
	v_readlane_b32 s21, v252, 13
	v_readlane_b32 s22, v252, 14
	v_readlane_b32 s23, v252, 15
	v_readlane_b32 s24, v252, 16
	v_readlane_b32 s25, v252, 17
	v_readlane_b32 s26, v252, 18
	v_readlane_b32 s27, v252, 19
	s_branch .LBB0_100

.LBB0_100:
	s_add_i32 s9, s12, s92
	s_cmpk_gt_i32 s9, 0x3ff
	s_cselect_b64 s[4:5], -1, 0
	s_and_b64 vcc, exec, s[4:5]
	s_waitcnt vmcnt(3)
	ds_write2_b32 v16, v0, v1 offset1:1
	ds_write2_b32 v16, v2, v3 offset0:2 offset1:3
	ds_write2_b32 v17, v4, v5 offset1:1
	ds_write2_b32 v17, v6, v7 offset0:2 offset1:3
	s_cbranch_vccnz .LBB0_99
	s_ashr_i32 s13, s9, 31
	s_lshr_b32 s13, s13, 23
	s_add_i32 s13, s9, s13
	s_ashr_i32 s14, s13, 9
	s_and_b32 s13, s13, 0xfe00
	s_sub_i32 s13, s9, s13
	s_sext_i32_i16 s15, s13
	s_bfe_u32 s15, s15, 0x5001a
	s_add_i32 s15, s13, s15
	s_sext_i32_i16 s16, s15
	s_and_b32 s15, s15, 0xffe0
	s_sub_i32 s13, s13, s15
	s_ashr_i32 s15, s14, 31
	s_lshl_b64 s[14:15], s[14:15], 24
	s_add_u32 s17, s7, s14
	s_sext_i32_i16 s13, s13
	s_addc_u32 s18, s8, s15
	s_lshl_b32 s14, s16, 1
	s_and_b32 s16, s14, 0xffffffc0
	s_lshl_b32 s14, s13, 6
	s_ashr_i32 s15, s14, 31
	s_lshl_b64 s[14:15], s[14:15], 2
	s_add_u32 s14, s17, s14
	v_add_u32_e32 v2, s16, v12
	s_addc_u32 s15, s18, s15
	v_mov_b32_e32 v11, v9
	v_ashrrev_i32_e32 v3, 31, v2
	v_lshl_add_u64 v[0:1], s[14:15], 0, v[10:11]
	v_lshlrev_b64 v[2:3], 14, v[2:3]
	v_lshl_add_u64 v[18:19], v[0:1], 0, v[2:3]
	v_add_u32_e32 v2, s16, v13
	v_ashrrev_i32_e32 v3, 31, v2
	v_lshlrev_b64 v[2:3], 14, v[2:3]
	v_lshl_add_u64 v[20:21], v[0:1], 0, v[2:3]
	global_load_dwordx4 v[0:3], v[18:19], off nt
	global_load_dwordx4 v[4:7], v[20:21], off nt
	s_add_i32 s94, s9, s92
	s_cmpk_gt_i32 s94, 0x3ff
	s_cselect_b32 s94, s9, s94
	s_ashr_i32 s13, s94, 31
	s_lshr_b32 s13, s13, 23
	s_add_i32 s13, s94, s13
	s_ashr_i32 s14, s13, 9
	s_and_b32 s13, s13, 0xfe00
	s_sub_i32 s13, s94, s13
	s_sext_i32_i16 s15, s13
	s_bfe_u32 s15, s15, 0x5001a
	s_add_i32 s15, s13, s15
	s_sext_i32_i16 s16, s15
	s_and_b32 s15, s15, 0xffe0
	s_sub_i32 s13, s13, s15
	s_ashr_i32 s15, s14, 31
	s_lshl_b64 s[14:15], s[14:15], 24
	s_add_u32 s17, s7, s14
	s_sext_i32_i16 s13, s13
	s_addc_u32 s18, s8, s15
	s_lshl_b32 s14, s16, 1
	s_and_b32 s16, s14, 0xffffffc0
	s_lshl_b32 s14, s13, 6
	s_ashr_i32 s15, s14, 31
	s_lshl_b64 s[14:15], s[14:15], 2
	s_add_u32 s14, s17, s14
	v_add_u32_e32 v42, s16, v12
	s_addc_u32 s15, s18, s15
	v_mov_b32_e32 v11, v9
	v_ashrrev_i32_e32 v43, 31, v42
	v_lshl_add_u64 v[40:41], s[14:15], 0, v[10:11]
	v_lshlrev_b64 v[42:43], 14, v[42:43]
	v_lshl_add_u64 v[44:45], v[40:41], 0, v[42:43]
	v_add_u32_e32 v42, s16, v13
	v_ashrrev_i32_e32 v43, 31, v42
	v_lshlrev_b64 v[42:43], 14, v[42:43]
	v_lshl_add_u64 v[46:47], v[40:41], 0, v[42:43]
	global_load_dword v48, v[44:45], off
	global_load_dword v49, v[46:47], off
	s_branch .LBB0_99
.LBB0_102:
	s_waitcnt vmcnt(0)
	s_add_u32 s64, s42, 0x9000000
	s_waitcnt vmcnt(0)
	v_cndmask_b32_e64 v0, 0, 1, s[0:1]
	s_addc_u32 s65, s43, 0
	v_mov_b32_e32 v10, v170
	v_cmp_ne_u32_e64 s[8:9], 1, v0
	s_andn2_b64 vcc, exec, s[0:1]
	s_cbranch_vccnz .LBB0_107
	s_ashr_i32 s0, s85, 31
	s_lshr_b32 s0, s0, 23
	s_add_i32 s1, s85, s0
	s_ashr_i32 s0, s1, 9
	s_and_b32 s1, s1, 0xfe00
	s_sub_i32 s1, s85, s1
	s_sext_i32_i16 s3, s1
	s_bfe_u32 s3, s3, 0x4001b
	s_add_i32 s3, s1, s3
	s_sext_i32_i16 s4, s3
	s_and_b32 s3, s3, 0xfff0
	s_sub_i32 s1, s1, s3
	s_sext_i32_i16 s3, s1
	s_ashr_i32 s1, s0, 31
	v_readlane_b32 s12, v252, 4
	s_lshl_b64 s[0:1], s[0:1], 23
	v_readlane_b32 s20, v252, 12
	v_readlane_b32 s21, v252, 13
	s_add_u32 s5, s20, s0
	s_addc_u32 s6, s21, s1
	s_lshl_b32 s0, s4, 2
	s_and_b32 s4, s0, 0xffffffc0
	s_lshl_b32 s0, s3, 6
	s_ashr_i32 s1, s0, 31
	s_lshl_b64 s[0:1], s[0:1], 2
	v_lshlrev_b32_e32 v0, 2, v10
	v_ashrrev_i32_e32 v12, 4, v10
	s_add_u32 s0, s5, s0
	v_and_b32_e32 v18, 60, v0
	v_add_u32_e32 v2, s4, v12
	s_addc_u32 s1, s6, s1
	v_mov_b32_e32 v9, 0
	v_lshlrev_b32_e32 v8, 2, v18
	v_ashrrev_i32_e32 v3, 31, v2
	v_lshl_add_u64 v[0:1], s[0:1], 0, v[8:9]
	v_lshlrev_b64 v[2:3], 12, v[2:3]
	v_lshl_add_u64 v[14:15], v[0:1], 0, v[2:3]
	v_add_u32_e32 v2, 0x200, v10
	v_ashrrev_i32_e32 v13, 4, v2
	v_add_u32_e32 v2, s4, v13
	v_ashrrev_i32_e32 v3, 31, v2
	v_lshlrev_b64 v[2:3], 12, v[2:3]
	v_lshl_add_u64 v[16:17], v[0:1], 0, v[2:3]
	global_load_dwordx4 v[0:3], v[14:15], off nt
	global_load_dwordx4 v[4:7], v[16:17], off nt
	global_load_dword v58, v[16:17], off
	global_load_dword v58, v[16:17], off
	global_load_dword v58, v[16:17], off
	v_add_u32_e32 v11, 0, v8
	v_lshlrev_b32_e32 v8, 3, v10
	v_ashrrev_i32_e32 v14, 3, v10
	v_and_b32_e32 v8, 56, v8
	s_movk_i32 s0, 0x104
	v_mul_u32_u24_e32 v10, 0x104, v8
	v_lshlrev_b32_e32 v15, 2, v14
	v_add3_u32 v15, 0, v10, v15
	v_mul_lo_u32 v10, v12, s0
	v_mul_lo_u32 v17, v13, s0
	v_add_u32_e32 v16, v11, v10
	v_add_u32_e32 v17, v11, v17
	v_lshlrev_b32_e32 v10, 2, v18
	v_lshlrev_b32_e32 v8, 1, v8
	s_mov_b32 s4, s85
	v_readlane_b32 s13, v252, 5
	v_readlane_b32 s14, v252, 6
	v_readlane_b32 s15, v252, 7
	v_readlane_b32 s16, v252, 8
	v_readlane_b32 s17, v252, 9
	v_readlane_b32 s18, v252, 10
	v_readlane_b32 s19, v252, 11
	v_readlane_b32 s22, v252, 14
	v_readlane_b32 s23, v252, 15
	v_readlane_b32 s24, v252, 16
	v_readlane_b32 s25, v252, 17
	v_readlane_b32 s26, v252, 18
	v_readlane_b32 s27, v252, 19
	s_branch .LBB0_105

.LBB0_105:
	s_add_i32 s3, s4, s92
	s_cmpk_gt_i32 s3, 0x3ff
	s_cselect_b64 s[0:1], -1, 0
	s_and_b64 vcc, exec, s[0:1]
	s_waitcnt vmcnt(4)
	ds_write2_b32 v16, v0, v1 offset1:1
	ds_write2_b32 v16, v2, v3 offset0:2 offset1:3
	s_waitcnt vmcnt(3)
	ds_write2_b32 v17, v4, v5 offset1:1
	ds_write2_b32 v17, v6, v7 offset0:2 offset1:3
	s_cbranch_vccnz .LBB0_104
	s_ashr_i32 s5, s3, 31
	s_lshr_b32 s5, s5, 23
	s_add_i32 s5, s3, s5
	s_ashr_i32 s6, s5, 9
	s_and_b32 s5, s5, 0xfe00
	s_sub_i32 s5, s3, s5
	s_sext_i32_i16 s7, s5
	s_bfe_u32 s7, s7, 0x4001b
	s_add_i32 s7, s5, s7
	s_sext_i32_i16 s12, s7
	s_and_b32 s7, s7, 0xfff0
	s_sub_i32 s5, s5, s7
	s_ashr_i32 s7, s6, 31
	v_readlane_b32 s16, v252, 4
	s_lshl_b64 s[6:7], s[6:7], 23
	v_readlane_b32 s24, v252, 12
	v_readlane_b32 s25, v252, 13
	s_add_u32 s13, s24, s6
	s_sext_i32_i16 s5, s5
	s_addc_u32 s14, s25, s7
	s_lshl_b32 s6, s12, 2
	s_and_b32 s12, s6, 0xffffffc0
	s_lshl_b32 s6, s5, 6
	s_ashr_i32 s7, s6, 31
	s_lshl_b64 s[6:7], s[6:7], 2
	s_add_u32 s6, s13, s6
	v_add_u32_e32 v2, s12, v12
	s_addc_u32 s7, s14, s7
	v_mov_b32_e32 v11, v9
	v_ashrrev_i32_e32 v3, 31, v2
	v_lshl_add_u64 v[0:1], s[6:7], 0, v[10:11]
	v_lshlrev_b64 v[2:3], 12, v[2:3]
	v_lshl_add_u64 v[18:19], v[0:1], 0, v[2:3]
	v_add_u32_e32 v2, s12, v13
	v_ashrrev_i32_e32 v3, 31, v2
	v_lshlrev_b64 v[2:3], 12, v[2:3]
	v_lshl_add_u64 v[20:21], v[0:1], 0, v[2:3]
	global_load_dwordx4 v[0:3], v[18:19], off nt
	global_load_dwordx4 v[4:7], v[20:21], off nt
	s_add_i32 s95, s3, s92
	s_cmpk_gt_i32 s95, 0x3ff
	s_cselect_b32 s95, s3, s95
	s_ashr_i32 s5, s95, 31
	s_lshr_b32 s5, s5, 23
	s_add_i32 s5, s95, s5
	s_ashr_i32 s6, s5, 9
	s_and_b32 s5, s5, 0xfe00
	s_sub_i32 s5, s95, s5
	s_sext_i32_i16 s7, s5
	s_bfe_u32 s7, s7, 0x4001b
	s_add_i32 s7, s5, s7
	s_sext_i32_i16 s12, s7
	s_and_b32 s7, s7, 0xfff0
	s_sub_i32 s5, s5, s7
	s_ashr_i32 s7, s6, 31
	v_readlane_b32 s16, v252, 4
	s_lshl_b64 s[6:7], s[6:7], 23
	v_readlane_b32 s24, v252, 12
	v_readlane_b32 s25, v252, 13
	s_add_u32 s13, s24, s6
	s_sext_i32_i16 s5, s5
	s_addc_u32 s14, s25, s7
	s_lshl_b32 s6, s12, 2
	s_and_b32 s12, s6, 0xffffffc0
	s_lshl_b32 s6, s5, 6
	s_ashr_i32 s7, s6, 31
	s_lshl_b64 s[6:7], s[6:7], 2
	s_add_u32 s6, s13, s6
	v_add_u32_e32 v52, s12, v12
	s_addc_u32 s7, s14, s7
	v_mov_b32_e32 v11, v9
	v_ashrrev_i32_e32 v53, 31, v52
	v_lshl_add_u64 v[50:51], s[6:7], 0, v[10:11]
	v_lshlrev_b64 v[52:53], 12, v[52:53]
	v_lshl_add_u64 v[54:55], v[50:51], 0, v[52:53]
	v_add_u32_e32 v52, s12, v13
	v_ashrrev_i32_e32 v53, 31, v52
	v_lshlrev_b64 v[52:53], 12, v[52:53]
	v_lshl_add_u64 v[56:57], v[50:51], 0, v[52:53]
	global_load_dword v58, v[54:55], off
	global_load_dword v59, v[56:57], off
	v_readlane_b32 s17, v252, 5
	v_readlane_b32 s18, v252, 6
	v_readlane_b32 s19, v252, 7
	v_readlane_b32 s20, v252, 8
	v_readlane_b32 s21, v252, 9
	v_readlane_b32 s22, v252, 10
	v_readlane_b32 s23, v252, 11
	v_readlane_b32 s26, v252, 14
	v_readlane_b32 s27, v252, 15
	v_readlane_b32 s28, v252, 16
	v_readlane_b32 s29, v252, 17
	v_readlane_b32 s30, v252, 18
	v_readlane_b32 s31, v252, 19
	s_branch .LBB0_104
.LBB0_107:
	s_waitcnt vmcnt(0)
	s_add_u32 s0, s42, 0xc000000
	s_addc_u32 s1, s43, 0
	v_writelane_b32 v252, s0, 22
	v_mov_b32_e32 v10, v170
	s_cmpk_gt_i32 s85, 0x5ff
	v_writelane_b32 v252, s1, 23
	s_cbranch_scc1 .LBB0_112
	s_mul_hi_i32 s0, s85, 0x2aaaaaab
	s_lshr_b32 s1, s0, 31
	s_lshr_b32 s0, s0, 8
	s_add_i32 s0, s0, s1
	s_mulk_i32 s0, 0x600
	s_sub_i32 s0, s85, s0
	s_mul_i32 s1, s0, 0x2aab
	s_lshr_b32 s3, s1, 31
	s_ashr_i32 s1, s1, 20
	s_add_i32 s1, s1, s3
	s_mul_i32 s3, s1, 0x60
	s_sub_i32 s0, s0, s3
	s_sext_i32_i16 s0, s0
	s_lshl_b32 s0, s0, 6
	s_lshl_b32 s4, s1, 6
	s_ashr_i32 s1, s0, 31
	v_readlane_b32 s12, v252, 4
	s_lshl_b64 s[0:1], s[0:1], 2
	v_readlane_b32 s22, v252, 14
	v_readlane_b32 s23, v252, 15
	s_add_u32 s0, s22, s0
	s_waitcnt vmcnt(2)
	v_lshlrev_b32_e32 v0, 4, v10
	s_addc_u32 s1, s23, s1
	v_and_b32_e32 v8, 0xf0, v0
	v_mov_b32_e32 v9, 0
	v_ashrrev_i32_e32 v12, 4, v10
	v_lshl_add_u64 v[0:1], s[0:1], 0, v[8:9]
	v_add_u32_e32 v2, s4, v12
	s_movk_i32 s3, 0x6000
	v_mad_i64_i32 v[14:15], s[0:1], v2, s3, v[0:1]
	v_add_u32_e32 v2, 0x200, v10
	v_ashrrev_i32_e32 v13, 4, v2
	v_add_u32_e32 v2, s4, v13
	v_mad_i64_i32 v[16:17], s[0:1], v2, s3, v[0:1]
	global_load_dwordx4 v[0:3], v[14:15], off nt
	global_load_dwordx4 v[4:7], v[16:17], off nt
	global_load_dword v68, v[16:17], off
	global_load_dword v68, v[16:17], off
	global_load_dword v68, v[16:17], off
	v_ashrrev_i32_e32 v14, 3, v10
	v_lshlrev_b32_e32 v10, 3, v10
	v_and_b32_e32 v18, 56, v10
	s_movk_i32 s0, 0x104
	v_mul_u32_u24_e32 v10, 0x104, v18
	v_lshlrev_b32_e32 v11, 2, v14
	v_add_u32_e32 v17, 0, v8
	v_add3_u32 v15, 0, v10, v11
	v_mul_lo_u32 v16, v12, s0
	v_mul_lo_u32 v19, v13, s0
	v_lshl_add_u64 v[10:11], s[22:23], 0, v[8:9]
	v_add_u32_e32 v16, v17, v16
	v_add_u32_e32 v17, v17, v19
	v_lshlrev_b32_e32 v8, 1, v18
	v_add_u32_e32 v18, 0x400, v15
	s_mov_b32 s5, s85
	v_readlane_b32 s13, v252, 5
	v_readlane_b32 s14, v252, 6
	v_readlane_b32 s15, v252, 7
	v_readlane_b32 s16, v252, 8
	v_readlane_b32 s17, v252, 9
	v_readlane_b32 s18, v252, 10
	v_readlane_b32 s19, v252, 11
	v_readlane_b32 s20, v252, 12
	v_readlane_b32 s21, v252, 13
	v_readlane_b32 s24, v252, 16
	v_readlane_b32 s25, v252, 17
	v_readlane_b32 s26, v252, 18
	v_readlane_b32 s27, v252, 19
	s_branch .LBB0_110

.LBB0_110:
	s_add_i32 s4, s5, s92
	s_cmpk_gt_i32 s4, 0x5ff
	s_cselect_b64 s[0:1], -1, 0
	s_and_b64 vcc, exec, s[0:1]
	s_waitcnt vmcnt(4)
	ds_write2_b32 v16, v0, v1 offset1:1
	ds_write2_b32 v16, v2, v3 offset0:2 offset1:3
	s_waitcnt vmcnt(3)
	ds_write2_b32 v17, v4, v5 offset1:1
	ds_write2_b32 v17, v6, v7 offset0:2 offset1:3
	s_cbranch_vccnz .LBB0_109
	s_mul_hi_i32 s6, s4, 0x2aaaaaab
	s_lshr_b32 s7, s6, 31
	s_lshr_b32 s6, s6, 8
	s_add_i32 s6, s6, s7
	s_mulk_i32 s6, 0x600
	s_sub_i32 s6, s4, s6
	s_sext_i32_i16 s7, s6
	s_mulk_i32 s7, 0x2aab
	s_lshr_b32 s12, s7, 31
	s_ashr_i32 s7, s7, 20
	s_add_i32 s7, s7, s12
	s_mul_i32 s12, s7, 0x60
	s_sub_i32 s6, s6, s12
	s_sext_i32_i16 s6, s6
	s_lshl_b32 s6, s6, 6
	s_lshl_b32 s12, s7, 6
	s_ashr_i32 s7, s6, 31
	v_lshl_add_u64 v[0:1], s[6:7], 2, v[10:11]
	v_add_u32_e32 v2, s12, v12
	v_mad_i64_i32 v[20:21], s[6:7], v2, s3, v[0:1]
	v_add_u32_e32 v2, s12, v13
	v_mad_i64_i32 v[22:23], s[6:7], v2, s3, v[0:1]
	global_load_dwordx4 v[0:3], v[20:21], off nt
	global_load_dwordx4 v[4:7], v[22:23], off nt
	s_add_i32 s94, s4, s92
	s_cmpk_gt_i32 s94, 0x5ff
	s_cselect_b32 s94, s4, s94
	s_mul_hi_i32 s6, s94, 0x2aaaaaab
	s_lshr_b32 s7, s6, 31
	s_lshr_b32 s6, s6, 8
	s_add_i32 s6, s6, s7
	s_mulk_i32 s6, 0x600
	s_sub_i32 s6, s94, s6
	s_sext_i32_i16 s7, s6
	s_mulk_i32 s7, 0x2aab
	s_lshr_b32 s12, s7, 31
	s_ashr_i32 s7, s7, 20
	s_add_i32 s7, s7, s12
	s_mul_i32 s12, s7, 0x60
	s_sub_i32 s6, s6, s12
	s_sext_i32_i16 s6, s6
	s_lshl_b32 s6, s6, 6
	s_lshl_b32 s12, s7, 6
	s_ashr_i32 s7, s6, 31
	v_lshl_add_u64 v[60:61], s[6:7], 2, v[10:11]
	v_add_u32_e32 v62, s12, v12
	v_mad_i64_i32 v[64:65], s[6:7], v62, s3, v[60:61]
	v_add_u32_e32 v62, s12, v13
	v_mad_i64_i32 v[66:67], s[6:7], v62, s3, v[60:61]
	global_load_dword v68, v[64:65], off
	global_load_dword v69, v[66:67], off
	s_branch .LBB0_109
.LBB0_112:
	s_waitcnt vmcnt(0)
	s_add_u32 s0, s42, 0xcc00000
	v_writelane_b32 v252, s0, 24
	s_addc_u32 s0, s43, 0
	v_writelane_b32 v252, s0, 25
	v_mov_b32_e32 v10, v170
	s_cmpk_gt_i32 s85, 0x7ff
	s_cbranch_scc1 .LBB0_117
	s_ashr_i32 s0, s85, 31
	s_lshr_b32 s0, s0, 22
	s_add_i32 s1, s85, s0
	s_ashr_i32 s0, s1, 10
	s_and_b32 s1, s1, 0xfc00
	s_sub_i32 s1, s85, s1
	s_sext_i32_i16 s3, s1
	s_bfe_u32 s3, s3, 0x60019
	s_add_i32 s3, s1, s3
	s_sext_i32_i16 s4, s3
	s_and_b32 s3, s3, 0xffc0
	s_sub_i32 s1, s1, s3
	s_sext_i32_i16 s3, s1
	s_ashr_i32 s1, s0, 31
	v_readlane_b32 s12, v252, 4
	s_lshl_b64 s[0:1], s[0:1], 24
	v_readlane_b32 s24, v252, 16
	v_readlane_b32 s25, v252, 17
	s_add_u32 s5, s24, s0
	s_addc_u32 s6, s25, s1
	s_lshl_b32 s0, s3, 6
	s_ashr_i32 s1, s0, 31
	s_andn2_b32 s4, s4, 63
	s_lshl_b64 s[0:1], s[0:1], 2
	s_waitcnt vmcnt(2)
	v_lshlrev_b32_e32 v0, 2, v10
	v_ashrrev_i32_e32 v12, 4, v10
	s_add_u32 s0, s5, s0
	v_and_b32_e32 v18, 60, v0
	v_add_u32_e32 v2, s4, v12
	s_addc_u32 s1, s6, s1
	v_mov_b32_e32 v9, 0
	v_lshlrev_b32_e32 v8, 2, v18
	v_ashrrev_i32_e32 v3, 31, v2
	v_lshl_add_u64 v[0:1], s[0:1], 0, v[8:9]
	v_lshlrev_b64 v[2:3], 14, v[2:3]
	v_lshl_add_u64 v[14:15], v[0:1], 0, v[2:3]
	v_add_u32_e32 v2, 0x200, v10
	v_ashrrev_i32_e32 v13, 4, v2
	v_add_u32_e32 v2, s4, v13
	v_ashrrev_i32_e32 v3, 31, v2
	v_lshlrev_b64 v[2:3], 14, v[2:3]
	v_lshl_add_u64 v[16:17], v[0:1], 0, v[2:3]
	global_load_dwordx4 v[0:3], v[14:15], off nt
	global_load_dwordx4 v[4:7], v[16:17], off nt
	global_load_dword v50, v[16:17], off
	global_load_dword v50, v[16:17], off
	global_load_dword v50, v[16:17], off
	v_add_u32_e32 v11, 0, v8
	v_lshlrev_b32_e32 v8, 3, v10
	v_ashrrev_i32_e32 v14, 3, v10
	v_and_b32_e32 v8, 56, v8
	s_movk_i32 s0, 0x104
	v_mul_u32_u24_e32 v10, 0x104, v8
	v_lshlrev_b32_e32 v15, 2, v14
	v_add3_u32 v15, 0, v10, v15
	v_mul_lo_u32 v10, v12, s0
	v_mul_lo_u32 v17, v13, s0
	v_add_u32_e32 v16, v11, v10
	v_add_u32_e32 v17, v11, v17
	v_lshlrev_b32_e32 v10, 2, v18
	v_lshlrev_b32_e32 v8, 1, v8
	s_mov_b32 s4, s85
	v_readlane_b32 s13, v252, 5
	v_readlane_b32 s14, v252, 6
	v_readlane_b32 s15, v252, 7
	v_readlane_b32 s16, v252, 8
	v_readlane_b32 s17, v252, 9
	v_readlane_b32 s18, v252, 10
	v_readlane_b32 s19, v252, 11
	v_readlane_b32 s20, v252, 12
	v_readlane_b32 s21, v252, 13
	v_readlane_b32 s22, v252, 14
	v_readlane_b32 s23, v252, 15
	v_readlane_b32 s26, v252, 18
	v_readlane_b32 s27, v252, 19
	s_branch .LBB0_115

.LBB0_115:
	s_add_i32 s3, s4, s92
	s_cmpk_gt_i32 s3, 0x7ff
	s_cselect_b64 s[0:1], -1, 0
	s_and_b64 vcc, exec, s[0:1]
	s_waitcnt vmcnt(4)
	ds_write2_b32 v16, v0, v1 offset1:1
	ds_write2_b32 v16, v2, v3 offset0:2 offset1:3
	s_waitcnt vmcnt(3)
	ds_write2_b32 v17, v4, v5 offset1:1
	ds_write2_b32 v17, v6, v7 offset0:2 offset1:3
	s_cbranch_vccnz .LBB0_114
	s_ashr_i32 s5, s3, 31
	s_lshr_b32 s5, s5, 22
	s_add_i32 s5, s3, s5
	s_ashr_i32 s6, s5, 10
	s_and_b32 s5, s5, 0xfc00
	s_sub_i32 s5, s3, s5
	s_sext_i32_i16 s7, s5
	s_bfe_u32 s7, s7, 0x60019
	s_add_i32 s7, s5, s7
	s_sext_i32_i16 s12, s7
	s_and_b32 s7, s7, 0xffc0
	s_sub_i32 s5, s5, s7
	s_ashr_i32 s7, s6, 31
	v_readlane_b32 s16, v252, 4
	s_lshl_b64 s[6:7], s[6:7], 24
	v_readlane_b32 s28, v252, 16
	s_sext_i32_i16 s5, s5
	v_readlane_b32 s29, v252, 17
	s_add_u32 s13, s28, s6
	s_addc_u32 s14, s29, s7
	s_lshl_b32 s6, s5, 6
	s_ashr_i32 s7, s6, 31
	s_andn2_b32 s12, s12, 63
	s_lshl_b64 s[6:7], s[6:7], 2
	s_add_u32 s6, s13, s6
	v_add_u32_e32 v2, s12, v12
	s_addc_u32 s7, s14, s7
	v_mov_b32_e32 v11, v9
	v_ashrrev_i32_e32 v3, 31, v2
	v_lshl_add_u64 v[0:1], s[6:7], 0, v[10:11]
	v_lshlrev_b64 v[2:3], 14, v[2:3]
	v_lshl_add_u64 v[18:19], v[0:1], 0, v[2:3]
	v_add_u32_e32 v2, s12, v13
	v_ashrrev_i32_e32 v3, 31, v2
	v_lshlrev_b64 v[2:3], 14, v[2:3]
	v_lshl_add_u64 v[20:21], v[0:1], 0, v[2:3]
	global_load_dwordx4 v[0:3], v[18:19], off nt
	global_load_dwordx4 v[4:7], v[20:21], off nt
	s_add_i32 s95, s3, s92
	s_cmpk_gt_i32 s95, 0x7ff
	s_cselect_b32 s95, s3, s95
	s_ashr_i32 s5, s95, 31
	s_lshr_b32 s5, s5, 22
	s_add_i32 s5, s95, s5
	s_ashr_i32 s6, s5, 10
	s_and_b32 s5, s5, 0xfc00
	s_sub_i32 s5, s95, s5
	s_sext_i32_i16 s7, s5
	s_bfe_u32 s7, s7, 0x60019
	s_add_i32 s7, s5, s7
	s_sext_i32_i16 s12, s7
	s_and_b32 s7, s7, 0xffc0
	s_sub_i32 s5, s5, s7
	s_ashr_i32 s7, s6, 31
	v_readlane_b32 s16, v252, 4
	s_lshl_b64 s[6:7], s[6:7], 24
	v_readlane_b32 s28, v252, 16
	s_sext_i32_i16 s5, s5
	v_readlane_b32 s29, v252, 17
	s_add_u32 s13, s28, s6
	s_addc_u32 s14, s29, s7
	s_lshl_b32 s6, s5, 6
	s_ashr_i32 s7, s6, 31
	s_andn2_b32 s12, s12, 63
	s_lshl_b64 s[6:7], s[6:7], 2
	s_add_u32 s6, s13, s6
	v_add_u32_e32 v44, s12, v12
	s_addc_u32 s7, s14, s7
	v_mov_b32_e32 v11, v9
	v_ashrrev_i32_e32 v45, 31, v44
	v_lshl_add_u64 v[42:43], s[6:7], 0, v[10:11]
	v_lshlrev_b64 v[44:45], 14, v[44:45]
	v_lshl_add_u64 v[46:47], v[42:43], 0, v[44:45]
	v_add_u32_e32 v44, s12, v13
	v_ashrrev_i32_e32 v45, 31, v44
	v_lshlrev_b64 v[44:45], 14, v[44:45]
	v_lshl_add_u64 v[48:49], v[42:43], 0, v[44:45]
	global_load_dword v50, v[46:47], off
	global_load_dword v51, v[48:49], off
	v_readlane_b32 s17, v252, 5
	v_readlane_b32 s18, v252, 6
	v_readlane_b32 s19, v252, 7
	v_readlane_b32 s20, v252, 8
	v_readlane_b32 s21, v252, 9
	v_readlane_b32 s22, v252, 10
	v_readlane_b32 s23, v252, 11
	v_readlane_b32 s24, v252, 12
	v_readlane_b32 s25, v252, 13
	v_readlane_b32 s26, v252, 14
	v_readlane_b32 s27, v252, 15
	v_readlane_b32 s30, v252, 18
	v_readlane_b32 s31, v252, 19
	s_branch .LBB0_114
.LBB0_117:
	s_waitcnt vmcnt(0)
	s_add_u32 s28, s42, 0xe000000
	s_addc_u32 s29, s43, 0
	s_waitcnt vmcnt(2)
	v_mov_b32_e32 v0, v170
	s_cmp_lt_u32 s85, 64
	s_cbranch_scc1 .LBB0_134
	s_add_i32 s0, s2, 0xffff8000
	v_add_u32_e32 v1, s0, v0
	s_mov_b32 s3, 0x200000
	v_cmp_gt_i32_e32 vcc, s3, v1
	s_and_saveexec_b64 s[6:7], vcc
	s_cbranch_execz .LBB0_133
	s_lshl_b32 s14, s92, 10
	v_add_u32_e32 v40, s2, v0
	s_lshl_b32 s2, s92, 11
	s_mul_i32 s15, s92, 0x600
	s_lshl_b32 s16, s92, 9
	v_mov_b32_e32 v0, 0
	s_add_i32 s14, s14, 0xfffe8000
	s_add_i32 s2, s2, 0xfffe0000
	s_add_i32 s15, s15, 0xfffe0000
	s_add_i32 s16, s16, 0xffff0000
	s_mov_b64 s[12:13], 0
	s_mov_b32 s17, 0x1fffff
	v_mov_b32_e32 v1, v0
	v_mov_b32_e32 v2, v0
	v_mov_b32_e32 v3, v0
	s_waitcnt vmcnt(1)
	v_mov_b32_e32 v4, v0
	v_mov_b32_e32 v5, v0
	v_mov_b32_e32 v6, v0
	v_mov_b32_e32 v7, v0
	v_mov_b32_e32 v12, v0
	v_mov_b32_e32 v13, v0
	v_mov_b32_e32 v14, v0
	v_mov_b32_e32 v15, v0
	v_mov_b32_e32 v8, v0
	v_mov_b32_e32 v9, v0
	v_mov_b32_e32 v10, v0
	v_mov_b32_e32 v11, v0
	v_mov_b32_e32 v16, v0
	v_mov_b32_e32 v17, v0
	v_mov_b32_e32 v18, v0
	v_mov_b32_e32 v19, v0
	v_mov_b32_e32 v20, v0
	v_mov_b32_e32 v21, v0
	v_mov_b32_e32 v22, v0
	v_mov_b32_e32 v23, v0
	s_branch .LBB0_121
